# A-attention loop: LDS-DMA via SGPR base + 32-bit lane offset (no per-step 64-bit VALU adds), DMA issue spread behind first MFMAs, single vmcnt(2) wait
# speedup vs baseline: 1.0246x; 1.0246x over previous
.LBB0_555:
	s_add_i32 s9, s43, 0xf000
.LBB0_557:
	ds_read_b128 v[32:35], v199 offset:20480
	ds_read_b128 v[42:45], v199 offset:24576
	s_add_u32 s4, s92, 0x15648000
	s_addc_u32 s5, s93, 0
	s_mov_b32 m0, s9
	s_nop 0
	global_load_lds_dwordx4 v164, s[4:5]
	s_waitcnt lgkmcnt(0)
	v_mfma_f32_32x32x16_bf16 v[112:127], v[32:35], v[132:135], v[48:63]
	ds_read_b128 v[38:41], v200 offset:20480
	ds_read_b128 v[188:191], v200 offset:24576
	s_setprio 1
	v_exp_f32_e32 v34, v80
	v_exp_f32_e32 v37, v81
	v_exp_f32_e32 v36, v82
	v_exp_f32_e32 v35, v83
	s_setprio 0
	s_add_u32 s4, s92, 0x16618180
	s_addc_u32 s5, s93, 0
	s_mov_b32 m0, s7
	s_nop 0
	global_load_lds_dwordx4 v160, s[4:5]
	s_waitcnt lgkmcnt(0)
	v_mfma_f32_32x32x16_bf16 v[112:127], v[38:41], v[128:131], v[112:127]
	ds_read_b128 v[80:83], v201 offset:20480
	ds_read_b128 v[220:223], v201 offset:24576
	s_setprio 1
	v_mfma_f32_32x32x16_bf16 v[96:111], v[42:45], v[132:135], v[48:63]
	v_exp_f32_e32 v32, v84
	v_exp_f32_e32 v41, v85
	v_exp_f32_e32 v40, v86
	v_exp_f32_e32 v33, v87
	s_setprio 0
	v_cvt_pk_bf16_f32 v84, v34, v37
	v_cvt_pk_bf16_f32 v85, v36, v35
	v_cvt_pk_bf16_f32 v86, v32, v41
	v_cvt_pk_bf16_f32 v87, v40, v33
	s_and_b64 vcc, exec, s[44:45]
	s_cbranch_vccnz .Lmy_a1_norope
	s_add_u32 s4, s92, 0x30e8500
	s_addc_u32 s5, s93, 0
	s_mov_b32 m0, s6
	s_nop 0
	global_load_lds_dwordx4 v162, s[4:5]
.Lmy_a1_norope:
	s_waitcnt lgkmcnt(0)
	v_mfma_f32_32x32x16_bf16 v[112:127], v[80:83], v[144:147], v[112:127]
	ds_read_b128 v[44:47], v202 offset:20480
	ds_read_b128 v[224:227], v202 offset:24576
	s_setprio 1
	v_exp_f32_e32 v38, v88
	v_exp_f32_e32 v43, v89
	v_exp_f32_e32 v42, v90
	v_exp_f32_e32 v39, v91
	s_setprio 0
	s_waitcnt lgkmcnt(0)
	v_mfma_f32_32x32x16_bf16 v[112:127], v[44:47], v[140:143], v[112:127]
	ds_read_b128 v[88:91], v210 offset:36864
	ds_read_b128 v[228:231], v210 offset:38912
	s_setprio 1
	v_mfma_f32_32x32x16_bf16 v[96:111], v[188:191], v[128:131], v[96:111]
	v_exp_f32_e32 v44, v92
	v_exp_f32_e32 v81, v93
	v_exp_f32_e32 v80, v94
	v_exp_f32_e32 v45, v95
	v_mfma_f32_32x32x16_bf16 v[96:111], v[220:223], v[144:147], v[96:111]
	s_setprio 0
	v_cvt_pk_bf16_f32 v92, v38, v43
	v_cvt_pk_bf16_f32 v93, v42, v39
	v_cvt_pk_bf16_f32 v94, v44, v81
	v_cvt_pk_bf16_f32 v95, v80, v45
	s_waitcnt lgkmcnt(0)
	v_mfma_f32_32x32x16_bf16 v[112:127], v[88:91], v[148:151], v[112:127]
	ds_read_b128 v[188:191], v211 offset:36864
	ds_read_b128 v[220:223], v211 offset:38912
	s_setprio 1
	v_exp_f32_e32 v46, v64
	v_exp_f32_e32 v83, v65
	v_exp_f32_e32 v82, v66
	v_exp_f32_e32 v47, v67
	s_setprio 0
	s_waitcnt lgkmcnt(0)
	v_mfma_f32_32x32x16_bf16 v[112:127], v[188:191], v[136:139], v[112:127]
	s_setprio 1
	v_mfma_f32_32x32x16_bf16 v[96:111], v[224:227], v[140:143], v[96:111]
	v_exp_f32_e32 v64, v68
	v_exp_f32_e32 v67, v69
	v_exp_f32_e32 v66, v70
	v_exp_f32_e32 v65, v71
	v_mfma_f32_32x32x16_bf16 v[96:111], v[228:231], v[148:151], v[96:111]
	s_setprio 0
	ds_read_b128 v[68:71], v206 offset:8192
	ds_read_b128 v[88:91], v206 offset:12288
	v_cvt_pk_bf16_f32 v188, v46, v83
	v_cvt_pk_bf16_f32 v189, v82, v47
	v_cvt_pk_bf16_f32 v190, v64, v67
	v_cvt_pk_bf16_f32 v191, v66, v65
	s_waitcnt lgkmcnt(0)
	v_mfma_f32_32x32x16_bf16 v[0:15], v[68:71], v[84:87], v[0:15]
	ds_read_b128 v[224:227], v205 offset:8192
	ds_read_b128 v[228:231], v205 offset:12288
	s_setprio 1
	v_exp_f32_e32 v68, v72
	v_exp_f32_e32 v71, v73
	v_exp_f32_e32 v70, v74
	v_exp_f32_e32 v69, v75
	s_setprio 0
	s_waitcnt lgkmcnt(0)
	v_mfma_f32_32x32x16_bf16 v[0:15], v[224:227], v[92:95], v[0:15]
	ds_read_b128 v[232:235], v204 offset:8192
	ds_read_b128 v[236:239], v204 offset:12288
	s_setprio 1
	v_mfma_f32_32x32x16_bf16 v[16:31], v[88:91], v[84:87], v[16:31]
	v_exp_f32_e32 v72, v76
	v_exp_f32_e32 v75, v77
	v_exp_f32_e32 v74, v78
	v_exp_f32_e32 v73, v79
	v_mfma_f32_32x32x16_bf16 v[96:111], v[220:223], v[136:139], v[96:111]
	v_mfma_f32_32x32x16_bf16 v[16:31], v[228:231], v[92:95], v[16:31]
	s_setprio 0
	v_cvt_pk_bf16_f32 v76, v68, v71
	v_cvt_pk_bf16_f32 v77, v70, v69
	v_cvt_pk_bf16_f32 v78, v72, v75
	v_cvt_pk_bf16_f32 v79, v74, v73
	s_waitcnt lgkmcnt(0)
	v_mfma_f32_32x32x16_bf16 v[0:15], v[232:235], v[188:191], v[0:15]
	ds_read_b128 v[84:87], v203 offset:8192
	ds_read_b128 v[88:91], v203 offset:12288
	v_max_f32_e32 v92, v112, v112
	v_max_f32_e32 v92, 0xf149f2ca, v92
	v_max3_f32 v93, v114, s72, v115
	v_max3_f32 v92, v92, v113, v116
	v_max3_f32 v93, v93, v118, v119
	v_max3_f32 v92, v92, v117, v120
	v_mfma_f32_32x32x16_bf16 v[16:31], v[236:239], v[188:191], v[16:31]
	v_max3_f32 v93, v93, v122, v123
	v_max3_f32 v92, v92, v121, v124
	v_max3_f32 v93, v93, v126, v127
	s_waitcnt lgkmcnt(0)
	v_mfma_f32_32x32x16_bf16 v[0:15], v[84:87], v[76:79], v[0:15]
	v_max3_f32 v84, v92, v125, v96
	v_max3_f32 v85, v93, v98, v99
	v_max3_f32 v84, v84, v97, v100
	v_max3_f32 v85, v85, v102, v103
	v_max3_f32 v84, v84, v101, v104
	v_max3_f32 v85, v85, v106, v107
	v_max3_f32 v84, v84, v105, v108
	v_mfma_f32_32x32x16_bf16 v[16:31], v[88:91], v[76:79], v[16:31]
	v_max3_f32 v85, v85, v110, v111
	v_max3_f32 v76, v84, v109, v85
	v_mov_b32_e32 v77, v76
	s_nop 1
	v_permlane32_swap_b32_e32 v76, v77
	s_waitcnt vmcnt(2)
.LBB0_559:
.LBB0_561:
	v_pk_add_f32 v[34:35], v[184:185], v[34:35]
	v_pk_add_f32 v[36:37], v[186:187], v[36:37]
	v_pk_add_f32 v[32:33], v[32:33], v[34:35]
	v_pk_add_f32 v[36:37], v[40:41], v[36:37]
	v_pk_add_f32 v[32:33], v[38:39], v[32:33]
	v_pk_add_f32 v[36:37], v[42:43], v[36:37]
	v_pk_add_f32 v[32:33], v[44:45], v[32:33]
	v_pk_add_f32 v[36:37], v[80:81], v[36:37]
	v_pk_add_f32 v[32:33], v[46:47], v[32:33]
	v_pk_add_f32 v[36:37], v[82:83], v[36:37]
	v_pk_add_f32 v[32:33], v[64:65], v[32:33]
	v_pk_add_f32 v[36:37], v[66:67], v[36:37]
	v_pk_add_f32 v[32:33], v[68:69], v[32:33]
	s_waitcnt lgkmcnt(0)
	s_barrier
	v_pk_add_f32 v[184:185], v[72:73], v[32:33]
	v_max_f32_e32 v32, v76, v76
	v_max_f32_e32 v33, v77, v77
	v_pk_add_f32 v[36:37], v[70:71], v[36:37]
	v_max_f32_e32 v32, v32, v33
	v_pk_add_f32 v[186:187], v[74:75], v[36:37]
	v_cmp_lt_f32_e32 vcc, s96, v32
	s_cbranch_vccz .LBB0_563
	v_max_f32_e32 v32, v32, v32
	v_max_f32_e32 v33, 0, v32
	v_exp_f32_e64 v34, -v33
	v_add_f32_e32 v209, v209, v33
	v_xor_b32_e32 v32, 0x80000000, v209
	v_sub_f32_e32 v127, v127, v33
	v_sub_f32_e32 v126, v126, v33
	v_sub_f32_e32 v125, v125, v33
	v_sub_f32_e32 v124, v124, v33
	v_sub_f32_e32 v123, v123, v33
	v_sub_f32_e32 v122, v122, v33
	v_sub_f32_e32 v121, v121, v33
	v_sub_f32_e32 v120, v120, v33
	v_sub_f32_e32 v119, v119, v33
	v_sub_f32_e32 v118, v118, v33
	v_sub_f32_e32 v117, v117, v33
	v_sub_f32_e32 v116, v116, v33
	v_sub_f32_e32 v115, v115, v33
	v_sub_f32_e32 v114, v114, v33
	v_sub_f32_e32 v113, v113, v33
	v_sub_f32_e32 v112, v112, v33
	v_sub_f32_e32 v111, v111, v33
	v_sub_f32_e32 v110, v110, v33
	v_sub_f32_e32 v109, v109, v33
	v_sub_f32_e32 v108, v108, v33
	v_sub_f32_e32 v107, v107, v33
	v_sub_f32_e32 v106, v106, v33
	v_sub_f32_e32 v105, v105, v33
	v_sub_f32_e32 v104, v104, v33
	v_sub_f32_e32 v103, v103, v33
	v_sub_f32_e32 v102, v102, v33
	v_sub_f32_e32 v101, v101, v33
	v_sub_f32_e32 v100, v100, v33
	v_sub_f32_e32 v99, v99, v33
	v_sub_f32_e32 v98, v98, v33
	v_sub_f32_e32 v97, v97, v33
	v_sub_f32_e32 v96, v96, v33
	v_pk_mul_f32 v[14:15], v[14:15], v[34:35] op_sel_hi:[1,0]
	v_pk_mul_f32 v[12:13], v[12:13], v[34:35] op_sel_hi:[1,0]
	v_pk_mul_f32 v[10:11], v[10:11], v[34:35] op_sel_hi:[1,0]
	v_pk_mul_f32 v[8:9], v[8:9], v[34:35] op_sel_hi:[1,0]
	v_pk_mul_f32 v[6:7], v[6:7], v[34:35] op_sel_hi:[1,0]
	v_pk_mul_f32 v[4:5], v[4:5], v[34:35] op_sel_hi:[1,0]
	v_pk_mul_f32 v[2:3], v[2:3], v[34:35] op_sel_hi:[1,0]
	v_pk_mul_f32 v[0:1], v[0:1], v[34:35] op_sel_hi:[1,0]
	v_pk_mul_f32 v[30:31], v[30:31], v[34:35] op_sel_hi:[1,0]
	v_pk_mul_f32 v[28:29], v[28:29], v[34:35] op_sel_hi:[1,0]
	v_pk_mul_f32 v[26:27], v[26:27], v[34:35] op_sel_hi:[1,0]
	v_pk_mul_f32 v[24:25], v[24:25], v[34:35] op_sel_hi:[1,0]
	v_pk_mul_f32 v[22:23], v[22:23], v[34:35] op_sel_hi:[1,0]
	v_pk_mul_f32 v[20:21], v[20:21], v[34:35] op_sel_hi:[1,0]
	v_pk_mul_f32 v[18:19], v[18:19], v[34:35] op_sel_hi:[1,0]
	v_pk_mul_f32 v[16:17], v[16:17], v[34:35] op_sel_hi:[1,0]
	v_pk_mul_f32 v[184:185], v[184:185], v[34:35] op_sel_hi:[1,0]
	v_pk_mul_f32 v[186:187], v[186:187], v[34:35] op_sel_hi:[1,0]
	v_mov_b32_e32 v33, v32
	v_mov_b32_e32 v34, v32
	v_mov_b32_e32 v35, v32
	v_mov_b32_e32 v36, v32
	v_mov_b32_e32 v37, v32
	v_mov_b32_e32 v38, v32
	v_mov_b32_e32 v39, v32
	v_mov_b32_e32 v40, v32
	v_mov_b32_e32 v41, v32
	v_mov_b32_e32 v42, v32
	v_mov_b32_e32 v43, v32
	v_mov_b32_e32 v44, v32
	v_mov_b32_e32 v45, v32
	v_mov_b32_e32 v46, v32
	v_mov_b32_e32 v47, v32
	v_mov_b32_e32 v48, v32
	v_mov_b32_e32 v49, v32
	v_mov_b32_e32 v50, v32
	v_mov_b32_e32 v51, v32
	v_mov_b32_e32 v52, v32
	v_mov_b32_e32 v53, v32
	v_mov_b32_e32 v54, v32
	v_mov_b32_e32 v55, v32
	v_mov_b32_e32 v56, v32
	v_mov_b32_e32 v57, v32
	v_mov_b32_e32 v58, v32
	v_mov_b32_e32 v59, v32
	v_mov_b32_e32 v60, v32
	v_mov_b32_e32 v61, v32
	v_mov_b32_e32 v62, v32
	v_mov_b32_e32 v63, v32
	s_branch .LBB0_564

.LBB0_564:
.LBB0_566:
	ds_read_b128 v[64:67], v199 offset:40960
	ds_read_b128 v[220:223], v199 offset:45056
	s_add_u32 s4, s92, 0x15658000
	s_addc_u32 s5, s93, 0
	s_mov_b32 m0, s43
	s_nop 0
	global_load_lds_dwordx4 v164, s[4:5]
	s_waitcnt lgkmcnt(0)
	v_mfma_f32_32x32x16_bf16 v[80:95], v[64:67], v[132:135], v[32:47]
	ds_read_b128 v[68:71], v200 offset:40960
	ds_read_b128 v[224:227], v200 offset:45056
	s_setprio 1
	v_exp_f32_e32 v112, v112
	v_exp_f32_e32 v189, v113
	v_exp_f32_e32 v188, v114
	v_exp_f32_e32 v113, v115
	s_setprio 0
	s_add_u32 s4, s92, 0x16618200
	s_addc_u32 s5, s93, 0
	s_mov_b32 m0, s70
	s_nop 0
	global_load_lds_dwordx4 v160, s[4:5]
	s_waitcnt lgkmcnt(0)
	v_mfma_f32_32x32x16_bf16 v[80:95], v[68:71], v[128:131], v[80:95]
	ds_read_b128 v[228:231], v201 offset:40960
	ds_read_b128 v[232:235], v201 offset:45056
	s_setprio 1
	v_mfma_f32_32x32x16_bf16 v[64:79], v[220:223], v[132:135], v[32:47]
	v_exp_f32_e32 v114, v116
	v_exp_f32_e32 v117, v117
	v_exp_f32_e32 v116, v118
	v_exp_f32_e32 v115, v119
	s_setprio 0
	v_cvt_pk_bf16_f32 v220, v112, v189
	v_cvt_pk_bf16_f32 v221, v188, v113
	v_cvt_pk_bf16_f32 v222, v114, v117
	v_cvt_pk_bf16_f32 v223, v116, v115
	s_and_b64 vcc, exec, s[44:45]
	s_cbranch_vccnz .Lmy_a2_norope
	s_add_u32 s4, s92, 0x31d8500
	s_addc_u32 s5, s93, 0
	s_add_i32 m0, s43, 0x4000
	s_nop 0
	global_load_lds_dwordx4 v162, s[4:5]
.Lmy_a2_norope:
	s_waitcnt lgkmcnt(0)
	v_mfma_f32_32x32x16_bf16 v[80:95], v[228:231], v[144:147], v[80:95]
	ds_read_b128 v[236:239], v202 offset:40960
	ds_read_b128 v[240:243], v202 offset:45056
	s_setprio 1
	v_exp_f32_e32 v118, v120
	v_exp_f32_e32 v191, v121
	v_exp_f32_e32 v190, v122
	v_exp_f32_e32 v119, v123
	s_setprio 0
	s_waitcnt lgkmcnt(0)
	v_mfma_f32_32x32x16_bf16 v[80:95], v[236:239], v[140:143], v[80:95]
	ds_read_b128 v[228:231], v210 offset:57344
	ds_read_b128 v[244:247], v210 offset:59392
	s_setprio 1
	v_mfma_f32_32x32x16_bf16 v[64:79], v[224:227], v[128:131], v[64:79]
	v_exp_f32_e32 v120, v124
	v_exp_f32_e32 v123, v125
	v_exp_f32_e32 v122, v126
	v_exp_f32_e32 v121, v127
	v_mfma_f32_32x32x16_bf16 v[64:79], v[232:235], v[144:147], v[64:79]
	s_setprio 0
	v_cvt_pk_bf16_f32 v224, v118, v191
	v_cvt_pk_bf16_f32 v225, v190, v119
	v_cvt_pk_bf16_f32 v226, v120, v123
	v_cvt_pk_bf16_f32 v227, v122, v121
	s_waitcnt lgkmcnt(0)
	v_mfma_f32_32x32x16_bf16 v[80:95], v[228:231], v[148:151], v[80:95]
	ds_read_b128 v[232:235], v211 offset:57344
	ds_read_b128 v[236:239], v211 offset:59392
	s_setprio 1
	v_exp_f32_e32 v96, v96
	v_exp_f32_e32 v125, v97
	v_exp_f32_e32 v124, v98
	v_exp_f32_e32 v97, v99
	s_setprio 0
	s_waitcnt lgkmcnt(0)
	v_mfma_f32_32x32x16_bf16 v[80:95], v[232:235], v[136:139], v[80:95]
	s_setprio 1
	v_mfma_f32_32x32x16_bf16 v[64:79], v[240:243], v[140:143], v[64:79]
	v_exp_f32_e32 v98, v100
	v_exp_f32_e32 v101, v101
	v_exp_f32_e32 v100, v102
	v_exp_f32_e32 v99, v103
	v_mfma_f32_32x32x16_bf16 v[64:79], v[244:247], v[148:151], v[64:79]
	s_setprio 0
	ds_read_b128 v[228:231], v206 offset:28672
	ds_read_b128 v[232:235], v206 offset:32768
	v_cvt_pk_bf16_f32 v240, v96, v125
	v_cvt_pk_bf16_f32 v241, v124, v97
	v_cvt_pk_bf16_f32 v242, v98, v101
	v_cvt_pk_bf16_f32 v243, v100, v99
	s_waitcnt lgkmcnt(0)
	v_mfma_f32_32x32x16_bf16 v[0:15], v[228:231], v[220:223], v[0:15]
	ds_read_b128 v[244:247], v205 offset:28672
	ds_read_b128 v[180:183], v205 offset:32768
	s_setprio 1
	v_exp_f32_e32 v102, v104
	v_exp_f32_e32 v105, v105
	v_exp_f32_e32 v104, v106
	v_exp_f32_e32 v103, v107
	s_setprio 0
	s_waitcnt lgkmcnt(0)
	v_mfma_f32_32x32x16_bf16 v[0:15], v[244:247], v[224:227], v[0:15]
	ds_read_b128 v[228:231], v204 offset:28672
	ds_read_b128 v[174:177], v204 offset:32768
	s_setprio 1
	v_mfma_f32_32x32x16_bf16 v[16:31], v[232:235], v[220:223], v[16:31]
	v_exp_f32_e32 v106, v108
	v_exp_f32_e32 v109, v109
	v_exp_f32_e32 v108, v110
	v_exp_f32_e32 v107, v111
	v_mfma_f32_32x32x16_bf16 v[64:79], v[236:239], v[136:139], v[64:79]
	v_mfma_f32_32x32x16_bf16 v[16:31], v[180:183], v[224:227], v[16:31]
	s_setprio 0
	v_cvt_pk_bf16_f32 v180, v102, v105
	v_cvt_pk_bf16_f32 v181, v104, v103
	v_cvt_pk_bf16_f32 v182, v106, v109
	v_cvt_pk_bf16_f32 v183, v108, v107
	s_waitcnt lgkmcnt(0)
	v_mfma_f32_32x32x16_bf16 v[0:15], v[228:231], v[240:243], v[0:15]
	ds_read_b128 v[220:223], v203 offset:28672
	ds_read_b128 v[224:227], v203 offset:32768
	v_max_f32_e32 v110, v80, v80
	v_max_f32_e32 v110, 0xf149f2ca, v110
	v_max3_f32 v111, v82, s72, v83
	v_max3_f32 v110, v110, v81, v84
	v_max3_f32 v111, v111, v86, v87
	v_max3_f32 v110, v110, v85, v88
	v_mfma_f32_32x32x16_bf16 v[16:31], v[174:177], v[240:243], v[16:31]
	v_max3_f32 v111, v111, v90, v91
	v_max3_f32 v110, v110, v89, v92
	v_max3_f32 v111, v111, v94, v95
	s_waitcnt lgkmcnt(0)
	v_mfma_f32_32x32x16_bf16 v[0:15], v[220:223], v[180:183], v[0:15]
	v_max3_f32 v110, v110, v93, v64
	v_max3_f32 v111, v111, v66, v67
	v_max3_f32 v110, v110, v65, v68
	v_max3_f32 v111, v111, v70, v71
	v_max3_f32 v110, v110, v69, v72
	v_max3_f32 v111, v111, v74, v75
	v_max3_f32 v110, v110, v73, v76
	v_mfma_f32_32x32x16_bf16 v[16:31], v[224:227], v[180:183], v[16:31]
	v_max3_f32 v111, v111, v78, v79
	v_max3_f32 v110, v110, v77, v111
	v_mov_b32_e32 v111, v110
	s_nop 1
	v_permlane32_swap_b32_e32 v110, v111
	s_waitcnt vmcnt(2)
.LBB0_568:
.LBB0_570:
	v_pk_add_f32 v[126:127], v[186:187], v[188:189]
	v_pk_add_f32 v[112:113], v[112:113], v[184:185]
	v_pk_add_f32 v[116:117], v[116:117], v[126:127]
	v_pk_add_f32 v[112:113], v[114:115], v[112:113]
	v_pk_add_f32 v[116:117], v[190:191], v[116:117]
	v_pk_add_f32 v[112:113], v[118:119], v[112:113]
	v_pk_add_f32 v[114:115], v[122:123], v[116:117]
	s_waitcnt lgkmcnt(0)
	s_barrier
	v_pk_add_f32 v[114:115], v[124:125], v[114:115]
	s_nop 0
	v_pk_add_f32 v[100:101], v[100:101], v[114:115]
	s_nop 0
	v_pk_add_f32 v[100:101], v[104:105], v[100:101]
	v_pk_add_f32 v[104:105], v[120:121], v[112:113]
	v_pk_add_f32 v[186:187], v[108:109], v[100:101]
	v_pk_add_f32 v[96:97], v[96:97], v[104:105]
	s_nop 0
	v_pk_add_f32 v[96:97], v[98:99], v[96:97]
	s_nop 0
	v_pk_add_f32 v[96:97], v[102:103], v[96:97]
	s_nop 0
	v_pk_add_f32 v[184:185], v[106:107], v[96:97]
	v_max_f32_e32 v96, v110, v110
	v_max_f32_e32 v97, v111, v111
	v_max_f32_e32 v96, v96, v97
	v_cmp_lt_f32_e32 vcc, s96, v96
	s_cbranch_vccz .LBB0_572
	v_max_f32_e32 v32, v96, v96
	v_max_f32_e32 v33, 0, v32
	v_exp_f32_e64 v34, -v33
	v_add_f32_e32 v209, v209, v33
	v_xor_b32_e32 v32, 0x80000000, v209
	v_sub_f32_e32 v95, v95, v33
	v_sub_f32_e32 v94, v94, v33
	v_sub_f32_e32 v93, v93, v33
	v_sub_f32_e32 v92, v92, v33
	v_sub_f32_e32 v91, v91, v33
	v_sub_f32_e32 v90, v90, v33
	v_sub_f32_e32 v89, v89, v33
	v_sub_f32_e32 v88, v88, v33
	v_sub_f32_e32 v87, v87, v33
	v_sub_f32_e32 v86, v86, v33
	v_sub_f32_e32 v85, v85, v33
	v_sub_f32_e32 v84, v84, v33
	v_sub_f32_e32 v83, v83, v33
	v_sub_f32_e32 v82, v82, v33
	v_sub_f32_e32 v81, v81, v33
	v_sub_f32_e32 v80, v80, v33
	v_sub_f32_e32 v79, v79, v33
	v_sub_f32_e32 v78, v78, v33
	v_sub_f32_e32 v77, v77, v33
	v_sub_f32_e32 v76, v76, v33
	v_sub_f32_e32 v75, v75, v33
	v_sub_f32_e32 v74, v74, v33
	v_sub_f32_e32 v73, v73, v33
	v_sub_f32_e32 v72, v72, v33
	v_sub_f32_e32 v71, v71, v33
	v_sub_f32_e32 v70, v70, v33
	v_sub_f32_e32 v69, v69, v33
	v_sub_f32_e32 v68, v68, v33
	v_sub_f32_e32 v67, v67, v33
	v_sub_f32_e32 v66, v66, v33
	v_sub_f32_e32 v65, v65, v33
	v_sub_f32_e32 v64, v64, v33
	v_pk_mul_f32 v[14:15], v[14:15], v[34:35] op_sel_hi:[1,0]
	v_pk_mul_f32 v[12:13], v[12:13], v[34:35] op_sel_hi:[1,0]
	v_pk_mul_f32 v[10:11], v[10:11], v[34:35] op_sel_hi:[1,0]
	v_pk_mul_f32 v[8:9], v[8:9], v[34:35] op_sel_hi:[1,0]
	v_pk_mul_f32 v[6:7], v[6:7], v[34:35] op_sel_hi:[1,0]
	v_pk_mul_f32 v[4:5], v[4:5], v[34:35] op_sel_hi:[1,0]
	v_pk_mul_f32 v[2:3], v[2:3], v[34:35] op_sel_hi:[1,0]
	v_pk_mul_f32 v[0:1], v[0:1], v[34:35] op_sel_hi:[1,0]
	v_pk_mul_f32 v[30:31], v[30:31], v[34:35] op_sel_hi:[1,0]
	v_pk_mul_f32 v[28:29], v[28:29], v[34:35] op_sel_hi:[1,0]
	v_pk_mul_f32 v[26:27], v[26:27], v[34:35] op_sel_hi:[1,0]
	v_pk_mul_f32 v[24:25], v[24:25], v[34:35] op_sel_hi:[1,0]
	v_pk_mul_f32 v[22:23], v[22:23], v[34:35] op_sel_hi:[1,0]
	v_pk_mul_f32 v[20:21], v[20:21], v[34:35] op_sel_hi:[1,0]
	v_pk_mul_f32 v[18:19], v[18:19], v[34:35] op_sel_hi:[1,0]
	v_pk_mul_f32 v[16:17], v[16:17], v[34:35] op_sel_hi:[1,0]
	v_pk_mul_f32 v[184:185], v[184:185], v[34:35] op_sel_hi:[1,0]
	v_pk_mul_f32 v[186:187], v[186:187], v[34:35] op_sel_hi:[1,0]
	v_mov_b32_e32 v33, v32
	v_mov_b32_e32 v34, v32
	v_mov_b32_e32 v35, v32
	v_mov_b32_e32 v36, v32
	v_mov_b32_e32 v37, v32
	v_mov_b32_e32 v38, v32
	v_mov_b32_e32 v39, v32
	v_mov_b32_e32 v40, v32
	v_mov_b32_e32 v41, v32
	v_mov_b32_e32 v42, v32
	v_mov_b32_e32 v43, v32
	v_mov_b32_e32 v44, v32
	v_mov_b32_e32 v45, v32
	v_mov_b32_e32 v46, v32
	v_mov_b32_e32 v47, v32
	v_mov_b32_e32 v48, v32
	v_mov_b32_e32 v49, v32
	v_mov_b32_e32 v50, v32
	v_mov_b32_e32 v51, v32
	v_mov_b32_e32 v52, v32
	v_mov_b32_e32 v53, v32
	v_mov_b32_e32 v54, v32
	v_mov_b32_e32 v55, v32
	v_mov_b32_e32 v56, v32
	v_mov_b32_e32 v57, v32
	v_mov_b32_e32 v58, v32
	v_mov_b32_e32 v59, v32
	v_mov_b32_e32 v60, v32
	v_mov_b32_e32 v61, v32
	v_mov_b32_e32 v62, v32
	v_mov_b32_e32 v63, v32
.LBB0_572:
.LBB0_574:
	s_add_i32 s10, 0, 0x10000
	v_add_u32_e32 v172, s10, v212
	ds_read_b128 v[96:99], v199 offset:61440
	ds_read_b128 v[174:177], v172
	s_add_u32 s4, s92, 0x15668000
	s_addc_u32 s5, s93, 0
	s_mov_b32 m0, s71
	s_nop 0
	global_load_lds_dwordx4 v164, s[4:5]
	s_waitcnt lgkmcnt(0)
	v_mfma_f32_32x32x16_bf16 v[112:127], v[96:99], v[132:135], v[32:47]
	v_add_u32_e32 v220, s10, v214
	ds_read_b128 v[100:103], v200 offset:61440
	ds_read_b128 v[180:183], v220
	s_setprio 1
	v_exp_f32_e32 v80, v80
	v_exp_f32_e32 v189, v81
	v_exp_f32_e32 v188, v82
	v_exp_f32_e32 v81, v83
	s_setprio 0
	s_add_u32 s4, s92, 0x16618280
	s_addc_u32 s5, s93, 0
	s_mov_b32 m0, s90
	s_nop 0
	global_load_lds_dwordx4 v160, s[4:5]
	s_waitcnt lgkmcnt(0)
	v_mfma_f32_32x32x16_bf16 v[112:127], v[100:103], v[128:131], v[112:127]
	v_add_u32_e32 v221, s10, v216
	ds_read_b128 v[224:227], v201 offset:61440
	ds_read_b128 v[228:231], v221
	s_setprio 1
	v_mfma_f32_32x32x16_bf16 v[96:111], v[174:177], v[132:135], v[32:47]
	v_exp_f32_e32 v82, v84
	v_exp_f32_e32 v191, v85
	v_exp_f32_e32 v190, v86
	v_exp_f32_e32 v83, v87
	s_setprio 0
	v_cvt_pk_bf16_f32 v174, v80, v189
	v_cvt_pk_bf16_f32 v175, v188, v81
	v_cvt_pk_bf16_f32 v176, v82, v191
	v_cvt_pk_bf16_f32 v177, v190, v83
	s_and_b64 vcc, exec, s[44:45]
	s_cbranch_vccnz .Lmy_a3_norope
	s_add_u32 s4, s92, 0x32c8500
	s_addc_u32 s5, s93, 0
	s_add_i32 m0, s43, 0x9000
	s_nop 0
	global_load_lds_dwordx4 v162, s[4:5]
.Lmy_a3_norope:
	s_waitcnt lgkmcnt(0)
	v_mfma_f32_32x32x16_bf16 v[112:127], v[224:227], v[144:147], v[112:127]
	v_add_u32_e32 v222, s10, v218
	ds_read_b128 v[232:235], v202 offset:61440
	ds_read_b128 v[236:239], v222
	s_setprio 1
	v_exp_f32_e32 v84, v88
	v_exp_f32_e32 v87, v89
	v_exp_f32_e32 v86, v90
	v_exp_f32_e32 v85, v91
	s_setprio 0
	s_waitcnt lgkmcnt(0)
	v_mfma_f32_32x32x16_bf16 v[112:127], v[232:235], v[140:143], v[112:127]
	ds_read_b128 v[224:227], v208 offset:61440
	ds_read_b128 v[240:243], v208 offset:63488
	s_setprio 1
	v_mfma_f32_32x32x16_bf16 v[96:111], v[180:183], v[128:131], v[96:111]
	v_exp_f32_e32 v88, v92
	v_exp_f32_e32 v91, v93
	v_exp_f32_e32 v90, v94
	v_exp_f32_e32 v89, v95
	v_mfma_f32_32x32x16_bf16 v[96:111], v[228:231], v[144:147], v[96:111]
	s_setprio 0
	v_cvt_pk_bf16_f32 v180, v84, v87
	v_cvt_pk_bf16_f32 v181, v86, v85
	v_cvt_pk_bf16_f32 v182, v88, v91
	v_cvt_pk_bf16_f32 v183, v90, v89
	s_waitcnt lgkmcnt(0)
	v_mfma_f32_32x32x16_bf16 v[112:127], v[224:227], v[148:151], v[112:127]
	ds_read_b128 v[228:231], v207 offset:61440
	ds_read_b128 v[232:235], v207 offset:63488
	s_setprio 1
	v_exp_f32_e32 v64, v64
	v_exp_f32_e32 v93, v65
	v_exp_f32_e32 v92, v66
	v_exp_f32_e32 v65, v67
	s_setprio 0
	s_waitcnt lgkmcnt(0)
	v_mfma_f32_32x32x16_bf16 v[112:127], v[228:231], v[136:139], v[112:127]
	s_setprio 1
	v_mfma_f32_32x32x16_bf16 v[96:111], v[236:239], v[140:143], v[96:111]
	v_exp_f32_e32 v66, v68
	v_exp_f32_e32 v69, v69
	v_exp_f32_e32 v68, v70
	v_exp_f32_e32 v67, v71
	v_mfma_f32_32x32x16_bf16 v[96:111], v[240:243], v[148:151], v[96:111]
	s_setprio 0
	ds_read_b128 v[224:227], v206 offset:49152
	ds_read_b128 v[228:231], v206 offset:53248
	v_cvt_pk_bf16_f32 v236, v64, v93
	v_cvt_pk_bf16_f32 v237, v92, v65
	v_cvt_pk_bf16_f32 v238, v66, v69
	v_cvt_pk_bf16_f32 v239, v68, v67
	s_waitcnt lgkmcnt(0)
	v_mfma_f32_32x32x16_bf16 v[0:15], v[224:227], v[174:177], v[0:15]
	ds_read_b128 v[240:243], v205 offset:49152
	ds_read_b128 v[244:247], v205 offset:53248
	s_setprio 1
	v_exp_f32_e32 v70, v72
	v_exp_f32_e32 v73, v73
	v_exp_f32_e32 v72, v74
	v_exp_f32_e32 v71, v75
	s_setprio 0
	s_waitcnt lgkmcnt(0)
	v_mfma_f32_32x32x16_bf16 v[0:15], v[240:243], v[180:183], v[0:15]
	ds_read_b128 v[224:227], v204 offset:49152
	ds_read_b128 v[192:195], v204 offset:53248
	s_setprio 1
	v_mfma_f32_32x32x16_bf16 v[16:31], v[228:231], v[174:177], v[16:31]
	v_exp_f32_e32 v74, v76
	v_exp_f32_e32 v77, v77
	v_exp_f32_e32 v76, v78
	v_exp_f32_e32 v75, v79
	v_mfma_f32_32x32x16_bf16 v[96:111], v[232:235], v[136:139], v[96:111]
	v_mfma_f32_32x32x16_bf16 v[16:31], v[244:247], v[180:183], v[16:31]
	s_setprio 0
	v_cvt_pk_bf16_f32 v174, v70, v73
	v_cvt_pk_bf16_f32 v175, v72, v71
	v_cvt_pk_bf16_f32 v176, v74, v77
	v_cvt_pk_bf16_f32 v177, v76, v75
	s_waitcnt lgkmcnt(0)
	v_mfma_f32_32x32x16_bf16 v[0:15], v[224:227], v[236:239], v[0:15]
	ds_read_b128 v[180:183], v203 offset:49152
	ds_read_b128 v[228:231], v203 offset:53248
	v_max_f32_e32 v78, v112, v112
	v_max_f32_e32 v78, 0xf149f2ca, v78
	v_max3_f32 v79, v114, s72, v115
	v_max3_f32 v78, v78, v113, v116
	v_max3_f32 v79, v79, v118, v119
	v_max3_f32 v78, v78, v117, v120
	v_mfma_f32_32x32x16_bf16 v[16:31], v[192:195], v[236:239], v[16:31]
	v_max3_f32 v79, v79, v122, v123
	v_max3_f32 v78, v78, v121, v124
	v_max3_f32 v79, v79, v126, v127
	s_waitcnt lgkmcnt(0)
	v_mfma_f32_32x32x16_bf16 v[0:15], v[180:183], v[174:177], v[0:15]
	v_max3_f32 v78, v78, v125, v96
	v_max3_f32 v79, v79, v98, v99
	v_max3_f32 v78, v78, v97, v100
	v_max3_f32 v79, v79, v102, v103
	v_max3_f32 v78, v78, v101, v104
	v_max3_f32 v79, v79, v106, v107
	v_max3_f32 v78, v78, v105, v108
	v_mfma_f32_32x32x16_bf16 v[16:31], v[228:231], v[174:177], v[16:31]
	v_max3_f32 v79, v79, v110, v111
	v_max3_f32 v78, v78, v109, v79
	v_mov_b32_e32 v79, v78
	s_nop 1
	v_permlane32_swap_b32_e32 v78, v79
	s_waitcnt vmcnt(2)
.LBB0_576:
.LBB0_578:
	v_pk_add_f32 v[80:81], v[80:81], v[184:185]
	v_pk_add_f32 v[94:95], v[186:187], v[188:189]
	v_pk_add_f32 v[80:81], v[82:83], v[80:81]
	v_pk_add_f32 v[94:95], v[190:191], v[94:95]
	v_pk_add_f32 v[80:81], v[84:85], v[80:81]
	v_pk_add_f32 v[86:87], v[86:87], v[94:95]
	v_pk_add_f32 v[80:81], v[88:89], v[80:81]
	v_pk_add_f32 v[86:87], v[90:91], v[86:87]
	v_pk_add_f32 v[64:65], v[64:65], v[80:81]
	v_pk_add_f32 v[86:87], v[92:93], v[86:87]
	v_pk_add_f32 v[64:65], v[66:67], v[64:65]
	v_pk_add_f32 v[68:69], v[68:69], v[86:87]
	v_pk_add_f32 v[64:65], v[70:71], v[64:65]
	s_waitcnt lgkmcnt(0)
	s_barrier
	v_pk_add_f32 v[184:185], v[74:75], v[64:65]
	v_max_f32_e32 v64, v78, v78
	v_max_f32_e32 v65, v79, v79
	v_pk_add_f32 v[68:69], v[72:73], v[68:69]
	v_max_f32_e32 v64, v64, v65
	v_pk_add_f32 v[186:187], v[76:77], v[68:69]
	v_cmp_lt_f32_e32 vcc, s96, v64
	s_cbranch_vccz .LBB0_580
	v_max_f32_e32 v32, v64, v64
	v_max_f32_e32 v33, 0, v32
	v_exp_f32_e64 v34, -v33
	v_add_f32_e32 v209, v209, v33
	v_xor_b32_e32 v32, 0x80000000, v209
	v_sub_f32_e32 v127, v127, v33
	v_sub_f32_e32 v126, v126, v33
	v_sub_f32_e32 v125, v125, v33
	v_sub_f32_e32 v124, v124, v33
	v_sub_f32_e32 v123, v123, v33
	v_sub_f32_e32 v122, v122, v33
	v_sub_f32_e32 v121, v121, v33
	v_sub_f32_e32 v120, v120, v33
	v_sub_f32_e32 v119, v119, v33
	v_sub_f32_e32 v118, v118, v33
	v_sub_f32_e32 v117, v117, v33
	v_sub_f32_e32 v116, v116, v33
	v_sub_f32_e32 v115, v115, v33
	v_sub_f32_e32 v114, v114, v33
	v_sub_f32_e32 v113, v113, v33
	v_sub_f32_e32 v112, v112, v33
	v_sub_f32_e32 v111, v111, v33
	v_sub_f32_e32 v110, v110, v33
	v_sub_f32_e32 v109, v109, v33
	v_sub_f32_e32 v108, v108, v33
	v_sub_f32_e32 v107, v107, v33
	v_sub_f32_e32 v106, v106, v33
	v_sub_f32_e32 v105, v105, v33
	v_sub_f32_e32 v104, v104, v33
	v_sub_f32_e32 v103, v103, v33
	v_sub_f32_e32 v102, v102, v33
	v_sub_f32_e32 v101, v101, v33
	v_sub_f32_e32 v100, v100, v33
	v_sub_f32_e32 v99, v99, v33
	v_sub_f32_e32 v98, v98, v33
	v_sub_f32_e32 v97, v97, v33
	v_sub_f32_e32 v96, v96, v33
	v_pk_mul_f32 v[14:15], v[14:15], v[34:35] op_sel_hi:[1,0]
	v_pk_mul_f32 v[12:13], v[12:13], v[34:35] op_sel_hi:[1,0]
	v_pk_mul_f32 v[10:11], v[10:11], v[34:35] op_sel_hi:[1,0]
	v_pk_mul_f32 v[8:9], v[8:9], v[34:35] op_sel_hi:[1,0]
	v_pk_mul_f32 v[6:7], v[6:7], v[34:35] op_sel_hi:[1,0]
	v_pk_mul_f32 v[4:5], v[4:5], v[34:35] op_sel_hi:[1,0]
	v_pk_mul_f32 v[2:3], v[2:3], v[34:35] op_sel_hi:[1,0]
	v_pk_mul_f32 v[0:1], v[0:1], v[34:35] op_sel_hi:[1,0]
	v_pk_mul_f32 v[30:31], v[30:31], v[34:35] op_sel_hi:[1,0]
	v_pk_mul_f32 v[28:29], v[28:29], v[34:35] op_sel_hi:[1,0]
	v_pk_mul_f32 v[26:27], v[26:27], v[34:35] op_sel_hi:[1,0]
	v_pk_mul_f32 v[24:25], v[24:25], v[34:35] op_sel_hi:[1,0]
	v_pk_mul_f32 v[22:23], v[22:23], v[34:35] op_sel_hi:[1,0]
	v_pk_mul_f32 v[20:21], v[20:21], v[34:35] op_sel_hi:[1,0]
	v_pk_mul_f32 v[18:19], v[18:19], v[34:35] op_sel_hi:[1,0]
	v_pk_mul_f32 v[16:17], v[16:17], v[34:35] op_sel_hi:[1,0]
	v_pk_mul_f32 v[184:185], v[184:185], v[34:35] op_sel_hi:[1,0]
	v_pk_mul_f32 v[186:187], v[186:187], v[34:35] op_sel_hi:[1,0]
	v_mov_b32_e32 v33, v32
	v_mov_b32_e32 v34, v32
	v_mov_b32_e32 v35, v32
	v_mov_b32_e32 v36, v32
	v_mov_b32_e32 v37, v32
	v_mov_b32_e32 v38, v32
	v_mov_b32_e32 v39, v32
	v_mov_b32_e32 v40, v32
	v_mov_b32_e32 v41, v32
	v_mov_b32_e32 v42, v32
	v_mov_b32_e32 v43, v32
	v_mov_b32_e32 v44, v32
	v_mov_b32_e32 v45, v32
	v_mov_b32_e32 v46, v32
	v_mov_b32_e32 v47, v32
	v_mov_b32_e32 v48, v32
	v_mov_b32_e32 v49, v32
	v_mov_b32_e32 v50, v32
	v_mov_b32_e32 v51, v32
	v_mov_b32_e32 v52, v32
	v_mov_b32_e32 v53, v32
	v_mov_b32_e32 v54, v32
	v_mov_b32_e32 v55, v32
	v_mov_b32_e32 v56, v32
	v_mov_b32_e32 v57, v32
	v_mov_b32_e32 v58, v32
	v_mov_b32_e32 v59, v32
	v_mov_b32_e32 v60, v32
	v_mov_b32_e32 v61, v32
	v_mov_b32_e32 v62, v32
	v_mov_b32_e32 v63, v32
.LBB0_580:
.LBB0_582:
	ds_read_b128 v[64:67], v199
	ds_read_b128 v[174:177], v199 offset:4096
	s_add_u32 s4, s92, 0x15678000
	s_addc_u32 s5, s93, 0
	s_mov_b32 m0, s91
	s_nop 0
	global_load_lds_dwordx4 v164, s[4:5]
	s_waitcnt lgkmcnt(0)
	v_mfma_f32_32x32x16_bf16 v[80:95], v[64:67], v[132:135], v[32:47]
	ds_read_b128 v[68:71], v200
	ds_read_b128 v[180:183], v200 offset:4096
	s_setprio 1
	v_exp_f32_e32 v112, v112
	v_exp_f32_e32 v167, v113
	v_exp_f32_e32 v166, v114
	v_exp_f32_e32 v113, v115
	s_setprio 0
	s_add_u32 s4, s92, 0x16618300
	s_addc_u32 s5, s93, 0
	s_mov_b32 m0, s95
	s_nop 0
	global_load_lds_dwordx4 v160, s[4:5]
	s_waitcnt lgkmcnt(0)
	v_mfma_f32_32x32x16_bf16 v[80:95], v[68:71], v[128:131], v[80:95]
	ds_read_b128 v[188:191], v201
	ds_read_b128 v[192:195], v201 offset:4096
	s_setprio 1
	v_mfma_f32_32x32x16_bf16 v[64:79], v[174:177], v[132:135], v[32:47]
	v_exp_f32_e32 v114, v116
	v_exp_f32_e32 v169, v117
	v_exp_f32_e32 v168, v118
	v_exp_f32_e32 v115, v119
	s_setprio 0
	v_cvt_pk_bf16_f32 v174, v112, v167
	v_cvt_pk_bf16_f32 v175, v166, v113
	v_cvt_pk_bf16_f32 v176, v114, v169
	v_cvt_pk_bf16_f32 v177, v168, v115
	s_and_b64 vcc, exec, s[44:45]
	s_cbranch_vccnz .Lmy_a4_norope
	s_add_u32 s4, s92, 0x33b8500
	s_addc_u32 s5, s93, 0
	s_add_i32 m0, s43, 0xe000
	s_nop 0
	global_load_lds_dwordx4 v162, s[4:5]
.Lmy_a4_norope:
	s_waitcnt lgkmcnt(0)
	v_mfma_f32_32x32x16_bf16 v[80:95], v[188:191], v[144:147], v[80:95]
	ds_read_b128 v[224:227], v202
	ds_read_b128 v[228:231], v202 offset:4096
	s_setprio 1
	v_exp_f32_e32 v116, v120
	v_exp_f32_e32 v121, v121
	v_exp_f32_e32 v120, v122
	v_exp_f32_e32 v117, v123
	s_setprio 0
	s_waitcnt lgkmcnt(0)
	v_mfma_f32_32x32x16_bf16 v[80:95], v[224:227], v[140:143], v[80:95]
	ds_read_b128 v[188:191], v210 offset:16384
	ds_read_b128 v[232:235], v210 offset:18432
	s_setprio 1
	v_mfma_f32_32x32x16_bf16 v[64:79], v[180:183], v[128:131], v[64:79]
	v_exp_f32_e32 v118, v124
	v_exp_f32_e32 v123, v125
	v_exp_f32_e32 v122, v126
	v_exp_f32_e32 v119, v127
	v_mfma_f32_32x32x16_bf16 v[64:79], v[192:195], v[144:147], v[64:79]
	s_setprio 0
	v_cvt_pk_bf16_f32 v180, v116, v121
	v_cvt_pk_bf16_f32 v181, v120, v117
	v_cvt_pk_bf16_f32 v182, v118, v123
	v_cvt_pk_bf16_f32 v183, v122, v119
	s_waitcnt lgkmcnt(0)
	v_mfma_f32_32x32x16_bf16 v[80:95], v[188:191], v[148:151], v[80:95]
	ds_read_b128 v[192:195], v211 offset:16384
	ds_read_b128 v[224:227], v211 offset:18432
	s_setprio 1
	v_exp_f32_e32 v96, v96
	v_exp_f32_e32 v125, v97
	v_exp_f32_e32 v124, v98
	v_exp_f32_e32 v97, v99
	s_setprio 0
	s_waitcnt lgkmcnt(0)
	v_mfma_f32_32x32x16_bf16 v[80:95], v[192:195], v[136:139], v[80:95]
	s_setprio 1
	v_mfma_f32_32x32x16_bf16 v[64:79], v[228:231], v[140:143], v[64:79]
	v_exp_f32_e32 v98, v100
	v_exp_f32_e32 v101, v101
	v_exp_f32_e32 v100, v102
	v_exp_f32_e32 v99, v103
	v_mfma_f32_32x32x16_bf16 v[64:79], v[232:235], v[148:151], v[64:79]
	s_setprio 0
	v_add_u32_e32 v170, 0, v213
	v_add_u32_e32 v171, s10, v213
	ds_read_b128 v[190:193], v170 offset:61440
	ds_read_b128 v[228:231], v171
	v_cvt_pk_bf16_f32 v232, v96, v125
	v_cvt_pk_bf16_f32 v233, v124, v97
	v_cvt_pk_bf16_f32 v234, v98, v101
	v_cvt_pk_bf16_f32 v235, v100, v99
	s_waitcnt lgkmcnt(0)
	v_mfma_f32_32x32x16_bf16 v[0:15], v[190:193], v[174:177], v[0:15]
	v_add_u32_e32 v188, 0, v215
	v_add_u32_e32 v189, s10, v215
	ds_read_b128 v[236:239], v188 offset:61440
	ds_read_b128 v[240:243], v189
	s_setprio 1
	v_exp_f32_e32 v102, v104
	v_exp_f32_e32 v105, v105
	v_exp_f32_e32 v104, v106
	v_exp_f32_e32 v103, v107
	s_setprio 0
	s_waitcnt lgkmcnt(0)
	v_mfma_f32_32x32x16_bf16 v[0:15], v[236:239], v[180:183], v[0:15]
	v_add_u32_e32 v190, 0, v217
	v_add_u32_e32 v191, s10, v217
	ds_read_b128 v[192:195], v190 offset:61440
	ds_read_b128 v[244:247], v191
	s_setprio 1
	v_mfma_f32_32x32x16_bf16 v[16:31], v[228:231], v[174:177], v[16:31]
	v_exp_f32_e32 v106, v108
	v_exp_f32_e32 v109, v109
	v_exp_f32_e32 v108, v110
	v_exp_f32_e32 v107, v111
	v_mfma_f32_32x32x16_bf16 v[64:79], v[224:227], v[136:139], v[64:79]
	v_mfma_f32_32x32x16_bf16 v[16:31], v[240:243], v[180:183], v[16:31]
	s_setprio 0
	v_cvt_pk_bf16_f32 v174, v102, v105
	v_cvt_pk_bf16_f32 v175, v104, v103
	v_cvt_pk_bf16_f32 v176, v106, v109
	v_cvt_pk_bf16_f32 v177, v108, v107
	s_waitcnt lgkmcnt(0)
	v_mfma_f32_32x32x16_bf16 v[0:15], v[192:195], v[232:235], v[0:15]
	v_add_u32_e32 v126, 0, v219
	v_add_u32_e32 v127, s10, v219
	v_max_f32_e32 v110, v80, v80
	ds_read_b128 v[180:183], v126 offset:61440
	ds_read_b128 v[224:227], v127
	v_max_f32_e32 v110, 0xf149f2ca, v110
	v_max3_f32 v111, v82, s72, v83
	v_mfma_f32_32x32x16_bf16 v[16:31], v[244:247], v[232:235], v[16:31]
	v_max3_f32 v110, v110, v81, v84
	v_max3_f32 v111, v111, v86, v87
	v_max3_f32 v110, v110, v85, v88
	v_max3_f32 v111, v111, v90, v91
	v_max3_f32 v110, v110, v89, v92
	v_max3_f32 v111, v111, v94, v95
	s_waitcnt lgkmcnt(0)
	v_mfma_f32_32x32x16_bf16 v[0:15], v[180:183], v[174:177], v[0:15]
	v_max3_f32 v110, v110, v93, v64
	v_max3_f32 v111, v111, v66, v67
	v_max3_f32 v110, v110, v65, v68
	v_max3_f32 v111, v111, v70, v71
	v_max3_f32 v110, v110, v69, v72
	v_max3_f32 v111, v111, v74, v75
	v_max3_f32 v110, v110, v73, v76
	v_mfma_f32_32x32x16_bf16 v[16:31], v[224:227], v[174:177], v[16:31]
	v_max3_f32 v111, v111, v78, v79
	v_max3_f32 v110, v110, v77, v111
	v_mov_b32_e32 v111, v110
	s_nop 1
	v_permlane32_swap_b32_e32 v110, v111
	s_waitcnt vmcnt(2)
.LBB0_584:
.LBB0_586:
	v_pk_add_f32 v[166:167], v[186:187], v[166:167]
	s_waitcnt lgkmcnt(0)
	s_barrier
	v_pk_add_f32 v[166:167], v[168:169], v[166:167]
	s_nop 0
	v_pk_add_f32 v[120:121], v[120:121], v[166:167]
	s_nop 0
	v_pk_add_f32 v[120:121], v[122:123], v[120:121]
	s_nop 0
	v_pk_add_f32 v[120:121], v[124:125], v[120:121]
	s_nop 0
	v_pk_add_f32 v[100:101], v[100:101], v[120:121]
	s_nop 0
	v_pk_add_f32 v[100:101], v[104:105], v[100:101]
	v_pk_add_f32 v[104:105], v[112:113], v[184:185]
	v_pk_add_f32 v[186:187], v[108:109], v[100:101]
	v_pk_add_f32 v[104:105], v[114:115], v[104:105]
	s_nop 0
	v_pk_add_f32 v[104:105], v[116:117], v[104:105]
	s_nop 0
	v_pk_add_f32 v[104:105], v[118:119], v[104:105]
	s_nop 0
	v_pk_add_f32 v[96:97], v[96:97], v[104:105]
	s_nop 0
	v_pk_add_f32 v[96:97], v[98:99], v[96:97]
	s_nop 0
	v_pk_add_f32 v[96:97], v[102:103], v[96:97]
	s_nop 0
	v_pk_add_f32 v[184:185], v[106:107], v[96:97]
	v_max_f32_e32 v96, v110, v110
	v_max_f32_e32 v97, v111, v111
	v_max_f32_e32 v96, v96, v97
	v_cmp_lt_f32_e32 vcc, s96, v96
	s_cbranch_vccz .LBB0_554
	v_max_f32_e32 v32, v96, v96
	v_max_f32_e32 v33, 0, v32
	v_exp_f32_e64 v34, -v33
	v_add_f32_e32 v209, v209, v33
	v_xor_b32_e32 v32, 0x80000000, v209
	v_sub_f32_e32 v95, v95, v33
	v_sub_f32_e32 v94, v94, v33
	v_sub_f32_e32 v93, v93, v33
	v_sub_f32_e32 v92, v92, v33
	v_sub_f32_e32 v91, v91, v33
	v_sub_f32_e32 v90, v90, v33
	v_sub_f32_e32 v89, v89, v33
	v_sub_f32_e32 v88, v88, v33
	v_sub_f32_e32 v87, v87, v33
	v_sub_f32_e32 v86, v86, v33
	v_sub_f32_e32 v85, v85, v33
	v_sub_f32_e32 v84, v84, v33
	v_sub_f32_e32 v83, v83, v33
	v_sub_f32_e32 v82, v82, v33
	v_sub_f32_e32 v81, v81, v33
	v_sub_f32_e32 v80, v80, v33
	v_sub_f32_e32 v79, v79, v33
	v_sub_f32_e32 v78, v78, v33
	v_sub_f32_e32 v77, v77, v33
	v_sub_f32_e32 v76, v76, v33
	v_sub_f32_e32 v75, v75, v33
	v_sub_f32_e32 v74, v74, v33
	v_sub_f32_e32 v73, v73, v33
	v_sub_f32_e32 v72, v72, v33
	v_sub_f32_e32 v71, v71, v33
	v_sub_f32_e32 v70, v70, v33
	v_sub_f32_e32 v69, v69, v33
	v_sub_f32_e32 v68, v68, v33
	v_sub_f32_e32 v67, v67, v33
	v_sub_f32_e32 v66, v66, v33
	v_sub_f32_e32 v65, v65, v33
	v_sub_f32_e32 v64, v64, v33
	v_pk_mul_f32 v[14:15], v[14:15], v[34:35] op_sel_hi:[1,0]
	v_pk_mul_f32 v[12:13], v[12:13], v[34:35] op_sel_hi:[1,0]
	v_pk_mul_f32 v[10:11], v[10:11], v[34:35] op_sel_hi:[1,0]
	v_pk_mul_f32 v[8:9], v[8:9], v[34:35] op_sel_hi:[1,0]
	v_pk_mul_f32 v[6:7], v[6:7], v[34:35] op_sel_hi:[1,0]
	v_pk_mul_f32 v[4:5], v[4:5], v[34:35] op_sel_hi:[1,0]
	v_pk_mul_f32 v[2:3], v[2:3], v[34:35] op_sel_hi:[1,0]
	v_pk_mul_f32 v[0:1], v[0:1], v[34:35] op_sel_hi:[1,0]
	v_pk_mul_f32 v[30:31], v[30:31], v[34:35] op_sel_hi:[1,0]
	v_pk_mul_f32 v[28:29], v[28:29], v[34:35] op_sel_hi:[1,0]
	v_pk_mul_f32 v[26:27], v[26:27], v[34:35] op_sel_hi:[1,0]
	v_pk_mul_f32 v[24:25], v[24:25], v[34:35] op_sel_hi:[1,0]
	v_pk_mul_f32 v[22:23], v[22:23], v[34:35] op_sel_hi:[1,0]
	v_pk_mul_f32 v[20:21], v[20:21], v[34:35] op_sel_hi:[1,0]
	v_pk_mul_f32 v[18:19], v[18:19], v[34:35] op_sel_hi:[1,0]
	v_pk_mul_f32 v[16:17], v[16:17], v[34:35] op_sel_hi:[1,0]
	v_pk_mul_f32 v[184:185], v[184:185], v[34:35] op_sel_hi:[1,0]
	v_pk_mul_f32 v[186:187], v[186:187], v[34:35] op_sel_hi:[1,0]
	v_mov_b32_e32 v33, v32
	v_mov_b32_e32 v34, v32
	v_mov_b32_e32 v35, v32
	v_mov_b32_e32 v36, v32
	v_mov_b32_e32 v37, v32
	v_mov_b32_e32 v38, v32
	v_mov_b32_e32 v39, v32
	v_mov_b32_e32 v40, v32
	v_mov_b32_e32 v41, v32
	v_mov_b32_e32 v42, v32
	v_mov_b32_e32 v43, v32
	v_mov_b32_e32 v44, v32
	v_mov_b32_e32 v45, v32
	v_mov_b32_e32 v46, v32
	v_mov_b32_e32 v47, v32
	v_mov_b32_e32 v48, v32
	v_mov_b32_e32 v49, v32
	v_mov_b32_e32 v50, v32
	v_mov_b32_e32 v51, v32
	v_mov_b32_e32 v52, v32
	v_mov_b32_e32 v53, v32
	v_mov_b32_e32 v54, v32
	v_mov_b32_e32 v55, v32
	v_mov_b32_e32 v56, v32
	v_mov_b32_e32 v57, v32
	v_mov_b32_e32 v58, v32
	v_mov_b32_e32 v59, v32
	v_mov_b32_e32 v60, v32
	v_mov_b32_e32 v61, v32
	v_mov_b32_e32 v62, v32
	v_mov_b32_e32 v63, v32
	s_branch .LBB0_554
